# attention queue: next claim requested one item ahead (atomic round trip under the item's operand loads)
# baseline (speedup 1.0000x reference)
; #define LAS __attribute__((address_space(3)))
; __device__ __forceinline__ void phase_attn(const Params& p, LAS unsigned char* lds) {
;     int tid_o = tid_of(p.wave_id);
;     const int tid = tid_o, lane = tid & 63, wave = __builtin_amdgcn_readfirstlane(tid >> 6);
;     const int qb = wave & 3, rw = wave >> 2, li = lane & 15, g = lane >> 4;
;     const bf16* QN = (const bf16*)(p.ws + WS_QN); const bf16* KN = (const bf16*)(p.ws + WS_KN); const bf16* VT = (const bf16*)(p.ws + WS_VN);
;     bf16* YB = (bf16*)p.out;
;     unsigned* ctr = (unsigned*)(p.ws + WS_ATTCTR);
;     LAS float* btab = (LAS float*)(lds + A_BIAS);
;     const float scale = 0.08838834764831845f * 1.4426950408889634f;
;     int krow_l[2], kch_l[2], vrow_l[2], vch_l[2];
; #pragma unroll
;     for (int e = 0; e < 2; ++e) { const int pk = 2 * wave + e; krow_l[e] = 4 * pk + (lane >> 4); kch_l[e] = (lane & 15) ^ (krow_l[e] & 15);
;         vrow_l[e] = 8 * pk + (lane >> 3); vch_l[e] = (lane & 7) ^ ((vrow_l[e] >> 1) & 7); }
;     const int myx = (int)(xb_xcc_id() & 7u);
;     int qoff = 0;
;     for (;;) {
;         if (tid == 0) { unsigned v = 0xffffffffu;
;             while (qoff < 8) { const int qx = (myx + qoff) & 7; const unsigned n = atomicAdd(ctr + 64 * qx, 1u); if (n < 64u) { v = (unsigned)((qx + 8 * (n >> 4)) * 16 + (n & 15)); break; } ++qoff; }
;             *(LAS unsigned*)(lds + A_ITEM) = v; }
;         __syncthreads();
;         const unsigned itu = *(LAS unsigned*)(lds + A_ITEM);
;         if (itu == 0xffffffffu) break;
;         const int it = (int)itu;
;         const int rp = it & 15, h = (it >> 4) & 7, b = it >> 7;
;         const int r = 2 * rp + rw;
;         const int rs = min(max(r - 4, 0), 24), ks0 = min(max(16 * qb - 8, 0), 32);
;         const int kr0 = min(max(2 * rp - 4, 0), 24), nband = min(max(2 * rp + 1 - 4, 0), 24) + 8 - kr0, NT = nband + 4;
;         const int cq = 16 * qb + li, cs = min(max(cq - 8, 0), 48);
;         const size_t qrow = (size_t)b * SEQ + r * GRID_W + cq;
;         float bvl = 0.f; if (tid < 15 * 31) bvl = p.rel_bias[h * 465 + tid];
;         bf16x8 qf[4];
; #pragma unroll
;         for (int ks = 0; ks < 4; ++ks) qf[ks] = *(const bf16x8*)(QN + qrow * WA + h * HD + 32 * ks + 8 * g);
;         const bf16* kg0 = KN + (size_t)h * HD + (size_t)krow_l[0] * WA + 8 * kch_l[0]; const bf16* kg1 = KN + (size_t)h * HD + (size_t)krow_l[1] * WA + 8 * kch_l[1];
.LBB0_436:
	s_waitcnt lgkmcnt(0)
	s_barrier
	s_waitcnt vmcnt(2)
	v_mbcnt_lo_u32_b32 v0, -1, 0
	v_mbcnt_hi_u32_b32 v0, -1, v0
	v_mov_b32_e32 v87, 0
	v_add_u32_e32 v85, s76, v0
	s_getreg_b32 s43, hwreg(HW_REG_XCC_ID, 0, 4)
	v_readfirstlane_b32 s34, v85
	s_ashr_i32 s3, s34, 6
	s_ashr_i32 s38, s34, 8
	s_add_u32 s39, s26, 0xdf42000
	s_addc_u32 s42, s27, 0
	s_lshl_b32 s4, s3, 1
	v_bfe_u32 v5, v85, 4, 2
	s_lshl_b32 s5, s3, 3
	s_or_b32 s4, s4, 1
	v_or_b32_e32 v0, s5, v5
	v_bitop3_b32 v3, s5, v85, v5 bitop3:0x36
	s_lshl_b32 s6, s3, 4
	s_lshl_b32 s5, s4, 2
	s_add_u32 s30, s26, 0xcf42000
	s_addc_u32 s31, s27, 0
	v_and_b32_e32 v10, 15, v85
	s_add_u32 s36, s26, 0xf142000
	v_bfe_u32 v1, v85, 3, 3
	s_addc_u32 s37, s27, 0
	v_lshlrev_b32_e32 v4, 3, v5
	s_waitcnt vmcnt(1)
	v_lshlrev_b32_e32 v15, 7, v10
	v_lshl_or_b32 v82, s4, 3, v1
	s_add_u32 s26, s26, 0x8000
	v_lshrrev_b32_e32 v13, 1, v85
	v_and_or_b32 v113, v4, 8, v15
	v_bfe_u32 v15, v85, 5, 1
	v_bitop3_b32 v19, v5, v10, 12 bitop3:0x36
	v_or_b32_e32 v80, s6, v1
	v_lshrrev_b32_e32 v1, 1, v82
	s_addc_u32 s27, s27, 0
	s_and_b32 s40, s6, 48
	v_bfe_u32 v6, v85, 1, 3
	v_lshlrev_b32_e32 v118, 4, v19
	v_bitop3_b32 v19, v13, v15, 7 bitop3:0x6c
	v_xor_b32_e32 v9, v1, v85
	v_sub_u32_e64 v1, s40, 8 clamp
	v_or_b32_e32 v84, s40, v10
	v_lshlrev_b32_e32 v119, 4, v19
	v_bitop3_b32 v19, v15, v6, 2 bitop3:0x36
	v_min_u32_e32 v11, 32, v1
	v_sub_u32_e64 v1, v84, 8 clamp
	v_lshlrev_b32_e32 v120, 4, v19
	v_bitop3_b32 v19, v15, v6, 4 bitop3:0x36
	v_bitop3_b32 v6, v15, v6, 6 bitop3:0x36
	v_min_u32_e32 v1, 48, v1
	v_lshlrev_b32_e32 v122, 4, v6
	v_lshlrev_b32_e32 v6, 2, v5
	v_lshlrev_b32_e32 v121, 4, v19
	v_add_u32_e32 v19, v11, v6
	v_add_u32_e32 v20, 16, v1
	v_cmp_ge_u32_e32 vcc, v19, v1
	v_cmp_lt_u32_e64 s[8:9], v19, v20
	v_or_b32_e32 v21, 1, v19
	s_and_b64 s[8:9], vcc, s[8:9]
	v_cmp_ge_u32_e32 vcc, v21, v1
	v_cmp_lt_u32_e64 s[10:11], v21, v20
	v_or_b32_e32 v21, 2, v19
	s_and_b64 s[10:11], vcc, s[10:11]
	v_cmp_ge_u32_e32 vcc, v21, v1
	v_cmp_lt_u32_e64 s[12:13], v21, v20
	v_or_b32_e32 v21, 3, v19
	s_and_b64 s[12:13], vcc, s[12:13]
	v_cmp_ge_u32_e32 vcc, v21, v1
	v_cmp_lt_u32_e64 s[14:15], v21, v20
	v_add_u32_e32 v21, 16, v19
	s_and_b64 s[14:15], vcc, s[14:15]
	v_cmp_ge_u32_e32 vcc, v21, v1
	v_cmp_lt_u32_e64 s[16:17], v19, v1
	v_add_u32_e32 v21, 17, v19
	s_and_b64 s[16:17], vcc, s[16:17]
	v_cmp_ge_u32_e32 vcc, v21, v1
	v_cmp_lt_u32_e64 s[18:19], v21, v20
	v_add_u32_e32 v21, 18, v19
	s_and_b64 s[18:19], vcc, s[18:19]
	v_cmp_ge_u32_e32 vcc, v21, v1
	v_cmp_lt_u32_e64 s[20:21], v21, v20
	v_add_u32_e32 v21, 19, v19
	s_and_b64 s[20:21], vcc, s[20:21]
	v_cmp_ge_u32_e32 vcc, v21, v1
	v_lshrrev_b32_e32 v1, 3, v11
	v_add_u32_e32 v1, v1, v15
	v_add_u32_e32 v15, 2, v1
	v_bitop3_b32 v1, v1, v13, 7 bitop3:0x78
	v_lshlrev_b32_e32 v123, 4, v1
	v_bitop3_b32 v1, v15, v13, 7 bitop3:0x78
	v_or_b32_e32 v2, s5, v5
	v_bitop3_b32 v8, s5, v85, v5 bitop3:0x36
	v_lshlrev_b32_e32 v124, 4, v1
	v_ashrrev_i32_e32 v1, 31, v0
	v_bitop3_b32 v7, v5, v85, 7 bitop3:0x78
	v_lshlrev_b64 v[88:89], 11, v[0:1]
	v_lshlrev_b32_e32 v0, 3, v3
	v_ashrrev_i32_e32 v3, 31, v2
	v_lshlrev_b32_e32 v1, 3, v8
	v_add_u32_e32 v12, v11, v10
	v_bitop3_b32 v16, v5, v85, 15 bitop3:0x78
	v_lshlrev_b64 v[90:91], 11, v[2:3]
	v_and_b32_e32 v2, 0x78, v1
	v_lshlrev_b32_e32 v86, 4, v7
	v_lshlrev_b32_e32 v1, 4, v9
	v_lshlrev_b32_e32 v14, 8, v12
	v_lshlrev_b32_e32 v115, 4, v16
	v_or_b32_e32 v16, 4, v5
	v_bitop3_b32 v17, v5, v10, 4 bitop3:0x36
	v_lshl_add_u64 v[92:93], s[36:37], 0, v[86:87]
	v_and_b32_e32 v86, 0x70, v1
	v_bitop3_b32 v1, v12, v5, 15 bitop3:0x6c
	v_lshlrev_b32_e32 v116, 4, v17
	v_or_b32_e32 v17, 8, v5
	v_bitop3_b32 v18, v5, v10, 8 bitop3:0x36
	v_lshl_or_b32 v125, v1, 4, v14
	v_bitop3_b32 v1, v12, v16, 15 bitop3:0x6c
	v_lshlrev_b32_e32 v117, 4, v18
	v_or_b32_e32 v18, 12, v5
	v_lshl_or_b32 v126, v1, 4, v14
	v_bitop3_b32 v1, v12, v17, 15 bitop3:0x6c
	v_lshl_or_b32 v127, v1, 4, v14
	v_bitop3_b32 v1, v12, v18, 15 bitop3:0x6c
	v_lshl_or_b32 v128, v1, 4, v14
	v_sub_u32_e32 v1, v19, v10
	v_subrev_u32_e32 v1, s40, v1
	v_lshlrev_b32_e32 v129, 2, v1
	v_and_b32_e32 v1, 48, v85
	v_lshl_add_u32 v1, v11, 2, v1
	v_lshlrev_b32_e32 v3, 2, v10
	s_lshl_b32 s3, s3, 11
	v_sub_u32_e32 v1, v1, v3
	s_and_b32 s34, s34, 0xc0
	s_movk_i32 s6, 0x1d1
	s_add_i32 s44, s3, 0
	s_add_i32 s3, 0, 0x20000
	v_cmp_lt_u32_e64 s[22:23], v21, v20
	v_and_b32_e32 v0, 0x78, v0
	v_subrev_u32_e32 v1, s34, v1
	s_mul_i32 s34, s38, 0x7c
	s_mov_b32 s35, 0
	v_cmp_eq_u32_e64 s[4:5], 0, v85
	v_cmp_gt_i32_e64 s[6:7], s6, v85
	s_add_i32 s45, s44, 0x8000
	v_lshl_add_u32 v112, v85, 2, s3
	v_lshlrev_b32_e32 v114, 8, v10
	s_and_b64 s[22:23], vcc, s[22:23]
	v_ashrrev_i32_e32 v81, 31, v80
	v_ashrrev_i32_e32 v83, 31, v82
	v_lshl_add_u64 v[94:95], s[36:37], 0, v[86:87]
	s_sub_i32 s37, 0, s38
	v_subrev_u32_e32 v130, s34, v1
	v_mov_b32_e32 v131, 1
	s_add_i32 s47, 0, 0x20800
	v_lshlrev_b32_e32 v86, 1, v4
	v_lshlrev_b32_e32 v96, 1, v0
	v_lshlrev_b32_e32 v98, 1, v2
	s_movk_i32 s49, 0x1200
	s_mov_b32 s36, 0x3e0293ee
	s_mov_b32 s62, 0xf149f2ca
	v_lshlrev_b32_e32 v100, 1, v6
	v_mov_b32_e32 v132, 0xf149f2ca
	v_mov_b32_e32 v133, v87
	s_mov_b32 s96, 0
	s_branch .LBB0_438

; #define LAS __attribute__((address_space(3)))
; __device__ __forceinline__ void phase_attn(const Params& p, LAS unsigned char* lds) {
;     ...
;         if (tid == 0) { unsigned v = 0xffffffffu;
;             while (qoff < 8) { const int qx = (myx + qoff) & 7; const unsigned n = atomicAdd(ctr + 64 * qx, 1u); if (n < 64u) { v = (unsigned)((qx + 8 * (n >> 4)) * 16 + (n & 15)); break; } ++qoff; }
;             *(LAS unsigned*)(lds + A_ITEM) = v; }
.Latt_claim:
	v_cmp_gt_i32_e32 vcc, 8, v133
	s_cbranch_vccz .Latt_claimed
	v_add_u32_e32 v1, s43, v133
	v_and_b32_e32 v1, 7, v1
	s_cmp_eq_u32 s96, 0
	s_cbranch_scc0 .Latt_have
	v_lshlrev_b32_e32 v2, 8, v1
	global_atomic_add v240, v2, v131, s[26:27] sc0
.Latt_have:
	s_mov_b32 s96, 0
	s_waitcnt vmcnt(0)
	v_cmp_gt_u32_e32 vcc, 64, v240
	s_cbranch_vccnz .Latt_got
	v_add_u32_e32 v133, 1, v133
	s_branch .Latt_claim
.Latt_got:
	v_lshrrev_b32_e32 v0, 1, v240
	v_and_or_b32 v0, v0, 24, v1
	v_and_b32_e32 v2, 15, v240
	v_lshl_or_b32 v0, v0, 4, v2
	v_lshlrev_b32_e32 v2, 8, v1
	global_atomic_add v240, v2, v131, s[26:27] sc0
	s_mov_b32 s96, 1
.Latt_claimed:
	v_mov_b32_e32 v1, s47
	ds_write_b32 v1, v0
